# S5: LDS fragment reads of the end-state and output GEMMs software-pipelined (ring of 8 quads, 4 ahead, counted lgkmcnt); gelu with folded constants as packed f32 pairs (two groups interleaved); gelu L
# speedup vs baseline: 1.1197x; 1.0053x over previous
.LBB0_495:
	s_waitcnt lgkmcnt(0)
	s_barrier
	ds_read_b128 v[212:215], v197
	ds_read_b128 v[216:219], v198
	ds_read_b128 v[220:223], v199
	ds_read_b128 v[228:231], v200
	ds_read_b128 v[232:235], v201
	s_waitcnt vmcnt(23)
	s_waitcnt lgkmcnt(4)
	v_mfma_f32_16x16x32_bf16 v[36:39], v[136:139], v[212:215], 0
	s_add_i32 s0, 0, 0x10000
	v_add3_u32 v184, s0, v196, v184
	v_lshlrev_b32_e32 v205, 3, v156
	s_waitcnt vmcnt(11)
	v_mfma_f32_16x16x32_bf16 v[32:35], v[152:155], v[212:215], 0
	s_ashr_i32 s22, s51, 5
	s_ashr_i32 s23, s22, 31
	s_lshl_b32 s0, s45, 20
	ds_read_b128 v[236:239], v202
	s_waitcnt lgkmcnt(4)
	v_mfma_f32_16x16x32_bf16 v[36:39], v[120:123], v[216:219], v[36:39]
	s_add_u32 s0, s16, s0
	s_addc_u32 s26, s17, 0
	s_lshl_b64 s[22:23], s[22:23], 16
	s_waitcnt vmcnt(10)
	v_mfma_f32_16x16x32_bf16 v[32:35], v[148:151], v[216:219], v[32:35]
	s_add_u32 s22, s0, s22
	s_addc_u32 s23, s26, s23
	ds_read_b128 v[240:243], v203
	s_waitcnt lgkmcnt(4)
	v_mfma_f32_16x16x32_bf16 v[36:39], v[108:111], v[220:223], v[36:39]
	s_add_i32 s43, s43, 1
	s_mov_b32 s51, s44
	s_waitcnt vmcnt(9)
	v_mfma_f32_16x16x32_bf16 v[32:35], v[144:147], v[220:223], v[32:35]
	ds_read_b128 v[244:247], v204
	s_waitcnt lgkmcnt(4)
	v_mfma_f32_16x16x32_bf16 v[36:39], v[100:103], v[228:231], v[36:39]
	s_waitcnt vmcnt(8)
	v_mfma_f32_16x16x32_bf16 v[32:35], v[140:143], v[228:231], v[32:35]
	ds_read_b128 v[212:215], v184
	s_waitcnt lgkmcnt(4)
	v_mfma_f32_16x16x32_bf16 v[36:39], v[92:95], v[232:235], v[36:39]
	s_waitcnt vmcnt(7)
	v_mfma_f32_16x16x32_bf16 v[32:35], v[132:135], v[232:235], v[32:35]
	ds_read_b128 v[216:219], v184 offset:64
	s_waitcnt lgkmcnt(4)
	v_mfma_f32_16x16x32_bf16 v[36:39], v[84:87], v[236:239], v[36:39]
	s_waitcnt vmcnt(6)
	v_mfma_f32_16x16x32_bf16 v[32:35], v[128:131], v[236:239], v[32:35]
	ds_read_b128 v[220:223], v184 offset:128
	s_waitcnt lgkmcnt(4)
	v_mfma_f32_16x16x32_bf16 v[36:39], v[80:83], v[240:243], v[36:39]
	s_waitcnt vmcnt(5)
	v_mfma_f32_16x16x32_bf16 v[32:35], v[124:127], v[240:243], v[32:35]
	ds_read_b128 v[228:231], v184 offset:192
	s_waitcnt lgkmcnt(4)
	v_mfma_f32_16x16x32_bf16 v[36:39], v[76:79], v[244:247], v[36:39]
	s_waitcnt vmcnt(4)
	v_mfma_f32_16x16x32_bf16 v[32:35], v[116:119], v[244:247], v[32:35]
	ds_read_b128 v[232:235], v197 offset:8192
	s_waitcnt lgkmcnt(4)
	v_mfma_f32_16x16x32_bf16 v[36:39], v[72:75], v[212:215], v[36:39]
	s_waitcnt vmcnt(3)
	v_mfma_f32_16x16x32_bf16 v[32:35], v[112:115], v[212:215], v[32:35]
	ds_read_b128 v[236:239], v198 offset:8192
	s_waitcnt lgkmcnt(4)
	v_mfma_f32_16x16x32_bf16 v[36:39], v[68:71], v[216:219], v[36:39]
	s_waitcnt vmcnt(2)
	v_mfma_f32_16x16x32_bf16 v[32:35], v[104:107], v[216:219], v[32:35]
	ds_read_b128 v[240:243], v199 offset:8192
	s_waitcnt lgkmcnt(4)
	v_mfma_f32_16x16x32_bf16 v[36:39], v[64:67], v[220:223], v[36:39]
	s_waitcnt vmcnt(1)
	v_mfma_f32_16x16x32_bf16 v[32:35], v[96:99], v[220:223], v[32:35]
	ds_read_b128 v[244:247], v200 offset:8192
	s_waitcnt lgkmcnt(4)
	v_mfma_f32_16x16x32_bf16 v[156:159], v[40:43], v[228:231], v[36:39]
	s_nop 2
	s_waitcnt vmcnt(0)
	v_mfma_f32_16x16x32_bf16 v[32:35], v[88:91], v[228:231], v[32:35]
	ds_read_b128 v[212:215], v201 offset:8192
	s_waitcnt lgkmcnt(4)
	v_mfma_f32_16x16x32_bf16 v[44:47], v[136:139], v[232:235], 0
	v_mfma_f32_16x16x32_bf16 v[36:39], v[152:155], v[232:235], 0
	ds_read_b128 v[216:219], v202 offset:8192
	s_waitcnt lgkmcnt(4)
	v_mfma_f32_16x16x32_bf16 v[44:47], v[120:123], v[236:239], v[44:47]
	v_mfma_f32_16x16x32_bf16 v[36:39], v[148:151], v[236:239], v[36:39]
	ds_read_b128 v[220:223], v203 offset:8192
	s_waitcnt lgkmcnt(4)
	v_mfma_f32_16x16x32_bf16 v[44:47], v[108:111], v[240:243], v[44:47]
	v_mfma_f32_16x16x32_bf16 v[36:39], v[144:147], v[240:243], v[36:39]
	ds_read_b128 v[228:231], v204 offset:8192
	s_waitcnt lgkmcnt(4)
	v_mfma_f32_16x16x32_bf16 v[44:47], v[100:103], v[244:247], v[44:47]
	v_mfma_f32_16x16x32_bf16 v[36:39], v[140:143], v[244:247], v[36:39]
	ds_read_b128 v[232:235], v184 offset:8192
	s_waitcnt lgkmcnt(4)
	v_mfma_f32_16x16x32_bf16 v[44:47], v[92:95], v[212:215], v[44:47]
	v_mfma_f32_16x16x32_bf16 v[36:39], v[132:135], v[212:215], v[36:39]
	ds_read_b128 v[236:239], v184 offset:8256
	s_waitcnt lgkmcnt(4)
	v_mfma_f32_16x16x32_bf16 v[44:47], v[84:87], v[216:219], v[44:47]
	v_mfma_f32_16x16x32_bf16 v[36:39], v[128:131], v[216:219], v[36:39]
	ds_read_b128 v[240:243], v184 offset:8320
	s_waitcnt lgkmcnt(4)
	v_mfma_f32_16x16x32_bf16 v[44:47], v[80:83], v[220:223], v[44:47]
	v_mfma_f32_16x16x32_bf16 v[36:39], v[124:127], v[220:223], v[36:39]
	ds_read_b128 v[244:247], v184 offset:8384
	s_waitcnt lgkmcnt(4)
	v_mfma_f32_16x16x32_bf16 v[44:47], v[76:79], v[228:231], v[44:47]
	v_mfma_f32_16x16x32_bf16 v[36:39], v[116:119], v[228:231], v[36:39]
	ds_read_b128 v[212:215], v197 offset:16384
	s_waitcnt lgkmcnt(4)
	v_mfma_f32_16x16x32_bf16 v[44:47], v[72:75], v[232:235], v[44:47]
	v_mfma_f32_16x16x32_bf16 v[36:39], v[112:115], v[232:235], v[36:39]
	ds_read_b128 v[216:219], v198 offset:16384
	s_waitcnt lgkmcnt(4)
	v_mfma_f32_16x16x32_bf16 v[44:47], v[68:71], v[236:239], v[44:47]
	v_mfma_f32_16x16x32_bf16 v[36:39], v[104:107], v[236:239], v[36:39]
	ds_read_b128 v[220:223], v199 offset:16384
	s_waitcnt lgkmcnt(4)
	v_mfma_f32_16x16x32_bf16 v[44:47], v[64:67], v[240:243], v[44:47]
	v_mfma_f32_16x16x32_bf16 v[36:39], v[96:99], v[240:243], v[36:39]
	ds_read_b128 v[228:231], v200 offset:16384
	s_waitcnt lgkmcnt(4)
	v_mfma_f32_16x16x32_bf16 v[172:175], v[40:43], v[244:247], v[44:47]
	v_mfma_f32_16x16x32_bf16 v[48:51], v[88:91], v[244:247], v[36:39]
	s_nop 3
	ds_read_b128 v[232:235], v201 offset:16384
	s_waitcnt lgkmcnt(4)
	v_mfma_f32_16x16x32_bf16 v[44:47], v[136:139], v[212:215], 0
	v_mfma_f32_16x16x32_bf16 v[36:39], v[152:155], v[212:215], 0
	ds_read_b128 v[236:239], v202 offset:16384
	s_waitcnt lgkmcnt(4)
	v_mfma_f32_16x16x32_bf16 v[44:47], v[120:123], v[216:219], v[44:47]
	v_mfma_f32_16x16x32_bf16 v[36:39], v[148:151], v[216:219], v[36:39]
	ds_read_b128 v[240:243], v203 offset:16384
	s_waitcnt lgkmcnt(4)
	v_mfma_f32_16x16x32_bf16 v[44:47], v[108:111], v[220:223], v[44:47]
	v_mfma_f32_16x16x32_bf16 v[36:39], v[144:147], v[220:223], v[36:39]
	ds_read_b128 v[244:247], v204 offset:16384
	s_waitcnt lgkmcnt(4)
	v_mfma_f32_16x16x32_bf16 v[44:47], v[100:103], v[228:231], v[44:47]
	v_mfma_f32_16x16x32_bf16 v[36:39], v[140:143], v[228:231], v[36:39]
	ds_read_b128 v[212:215], v184 offset:16384
	s_waitcnt lgkmcnt(4)
	v_mfma_f32_16x16x32_bf16 v[44:47], v[92:95], v[232:235], v[44:47]
	v_mfma_f32_16x16x32_bf16 v[36:39], v[132:135], v[232:235], v[36:39]
	ds_read_b128 v[216:219], v184 offset:16448
	s_waitcnt lgkmcnt(4)
	v_mfma_f32_16x16x32_bf16 v[44:47], v[84:87], v[236:239], v[44:47]
	v_mfma_f32_16x16x32_bf16 v[36:39], v[128:131], v[236:239], v[36:39]
	ds_read_b128 v[220:223], v184 offset:16512
	s_waitcnt lgkmcnt(4)
	v_mfma_f32_16x16x32_bf16 v[44:47], v[80:83], v[240:243], v[44:47]
	v_mfma_f32_16x16x32_bf16 v[36:39], v[124:127], v[240:243], v[36:39]
	ds_read_b128 v[228:231], v184 offset:16576
	s_waitcnt lgkmcnt(4)
	v_mfma_f32_16x16x32_bf16 v[44:47], v[76:79], v[244:247], v[44:47]
	v_mfma_f32_16x16x32_bf16 v[36:39], v[116:119], v[244:247], v[36:39]
	ds_read_b128 v[232:235], v197 offset:24576
	s_waitcnt lgkmcnt(4)
	v_mfma_f32_16x16x32_bf16 v[44:47], v[72:75], v[212:215], v[44:47]
	v_mfma_f32_16x16x32_bf16 v[36:39], v[112:115], v[212:215], v[36:39]
	ds_read_b128 v[236:239], v198 offset:24576
	s_waitcnt lgkmcnt(4)
	v_mfma_f32_16x16x32_bf16 v[44:47], v[68:71], v[216:219], v[44:47]
	v_mfma_f32_16x16x32_bf16 v[36:39], v[104:107], v[216:219], v[36:39]
	ds_read_b128 v[240:243], v199 offset:24576
	s_waitcnt lgkmcnt(4)
	v_mfma_f32_16x16x32_bf16 v[44:47], v[64:67], v[220:223], v[44:47]
	v_mfma_f32_16x16x32_bf16 v[36:39], v[96:99], v[220:223], v[36:39]
	ds_read_b128 v[244:247], v200 offset:24576
	s_waitcnt lgkmcnt(4)
	v_mfma_f32_16x16x32_bf16 v[160:163], v[40:43], v[228:231], v[44:47]
	s_nop 3
	v_mfma_f32_16x16x32_bf16 v[36:39], v[88:91], v[228:231], v[36:39]
	ds_read_b128 v[212:215], v201 offset:24576
	s_waitcnt lgkmcnt(4)
	v_mfma_f32_16x16x32_bf16 v[52:55], v[136:139], v[232:235], 0
	v_mfma_f32_16x16x32_bf16 v[44:47], v[152:155], v[232:235], 0
	ds_read_b128 v[216:219], v202 offset:24576
	s_waitcnt lgkmcnt(4)
	v_mfma_f32_16x16x32_bf16 v[52:55], v[120:123], v[236:239], v[52:55]
	v_mfma_f32_16x16x32_bf16 v[44:47], v[148:151], v[236:239], v[44:47]
	ds_read_b128 v[220:223], v203 offset:24576
	s_waitcnt lgkmcnt(4)
	v_mfma_f32_16x16x32_bf16 v[52:55], v[108:111], v[240:243], v[52:55]
	v_mfma_f32_16x16x32_bf16 v[44:47], v[144:147], v[240:243], v[44:47]
	ds_read_b128 v[228:231], v204 offset:24576
	s_waitcnt lgkmcnt(4)
	v_mfma_f32_16x16x32_bf16 v[52:55], v[100:103], v[244:247], v[52:55]
	v_mfma_f32_16x16x32_bf16 v[44:47], v[140:143], v[244:247], v[44:47]
	ds_read_b128 v[232:235], v184 offset:24576
	s_waitcnt lgkmcnt(4)
	v_mfma_f32_16x16x32_bf16 v[52:55], v[92:95], v[212:215], v[52:55]
	v_mfma_f32_16x16x32_bf16 v[44:47], v[132:135], v[212:215], v[44:47]
	ds_read_b128 v[236:239], v184 offset:24640
	s_waitcnt lgkmcnt(4)
	v_mfma_f32_16x16x32_bf16 v[52:55], v[84:87], v[216:219], v[52:55]
	v_mfma_f32_16x16x32_bf16 v[44:47], v[128:131], v[216:219], v[44:47]
	ds_read_b128 v[240:243], v184 offset:24704
	s_waitcnt lgkmcnt(4)
	v_mfma_f32_16x16x32_bf16 v[52:55], v[80:83], v[220:223], v[52:55]
	v_mfma_f32_16x16x32_bf16 v[44:47], v[124:127], v[220:223], v[44:47]
	ds_read_b128 v[244:247], v184 offset:24768
	s_waitcnt lgkmcnt(4)
	v_mfma_f32_16x16x32_bf16 v[52:55], v[76:79], v[228:231], v[52:55]
	v_mfma_f32_16x16x32_bf16 v[44:47], v[116:119], v[228:231], v[44:47]
	ds_read_b128 v[212:215], v197 offset:32768
	s_waitcnt lgkmcnt(4)
	v_mfma_f32_16x16x32_bf16 v[52:55], v[72:75], v[232:235], v[52:55]
	v_mfma_f32_16x16x32_bf16 v[44:47], v[112:115], v[232:235], v[44:47]
	ds_read_b128 v[216:219], v198 offset:32768
	s_waitcnt lgkmcnt(4)
	v_mfma_f32_16x16x32_bf16 v[52:55], v[68:71], v[236:239], v[52:55]
	v_mfma_f32_16x16x32_bf16 v[44:47], v[104:107], v[236:239], v[44:47]
	ds_read_b128 v[220:223], v199 offset:32768
	s_waitcnt lgkmcnt(4)
	v_mfma_f32_16x16x32_bf16 v[52:55], v[64:67], v[240:243], v[52:55]
	v_mfma_f32_16x16x32_bf16 v[44:47], v[96:99], v[240:243], v[44:47]
	ds_read_b128 v[228:231], v200 offset:32768
	s_waitcnt lgkmcnt(4)
	v_mfma_f32_16x16x32_bf16 v[60:63], v[88:91], v[244:247], v[44:47]
	s_nop 4
	v_mfma_f32_16x16x32_bf16 v[180:183], v[40:43], v[244:247], v[52:55]
	ds_read_b128 v[232:235], v201 offset:32768
	s_waitcnt lgkmcnt(4)
	v_mfma_f32_16x16x32_bf16 v[52:55], v[136:139], v[212:215], 0
	v_mfma_f32_16x16x32_bf16 v[44:47], v[152:155], v[212:215], 0
	ds_read_b128 v[236:239], v202 offset:32768
	s_waitcnt lgkmcnt(4)
	v_mfma_f32_16x16x32_bf16 v[52:55], v[120:123], v[216:219], v[52:55]
	v_mfma_f32_16x16x32_bf16 v[44:47], v[148:151], v[216:219], v[44:47]
	ds_read_b128 v[240:243], v203 offset:32768
	s_waitcnt lgkmcnt(4)
	v_mfma_f32_16x16x32_bf16 v[52:55], v[108:111], v[220:223], v[52:55]
	v_mfma_f32_16x16x32_bf16 v[44:47], v[144:147], v[220:223], v[44:47]
	ds_read_b128 v[244:247], v204 offset:32768
	s_waitcnt lgkmcnt(4)
	v_mfma_f32_16x16x32_bf16 v[52:55], v[100:103], v[228:231], v[52:55]
	v_mfma_f32_16x16x32_bf16 v[44:47], v[140:143], v[228:231], v[44:47]
	ds_read_b128 v[212:215], v184 offset:32768
	s_waitcnt lgkmcnt(4)
	v_mfma_f32_16x16x32_bf16 v[52:55], v[92:95], v[232:235], v[52:55]
	v_mfma_f32_16x16x32_bf16 v[44:47], v[132:135], v[232:235], v[44:47]
	ds_read_b128 v[216:219], v184 offset:32832
	s_waitcnt lgkmcnt(4)
	v_mfma_f32_16x16x32_bf16 v[52:55], v[84:87], v[236:239], v[52:55]
	v_mfma_f32_16x16x32_bf16 v[44:47], v[128:131], v[236:239], v[44:47]
	ds_read_b128 v[220:223], v184 offset:32896
	s_waitcnt lgkmcnt(4)
	v_mfma_f32_16x16x32_bf16 v[52:55], v[80:83], v[240:243], v[52:55]
	v_mfma_f32_16x16x32_bf16 v[44:47], v[124:127], v[240:243], v[44:47]
	ds_read_b128 v[228:231], v184 offset:32960
	s_waitcnt lgkmcnt(4)
	v_mfma_f32_16x16x32_bf16 v[52:55], v[76:79], v[244:247], v[52:55]
	v_mfma_f32_16x16x32_bf16 v[44:47], v[116:119], v[244:247], v[44:47]
	ds_read_b128 v[232:235], v197 offset:40960
	s_waitcnt lgkmcnt(4)
	v_mfma_f32_16x16x32_bf16 v[52:55], v[72:75], v[212:215], v[52:55]
	v_mfma_f32_16x16x32_bf16 v[44:47], v[112:115], v[212:215], v[44:47]
	ds_read_b128 v[236:239], v198 offset:40960
	s_waitcnt lgkmcnt(4)
	v_mfma_f32_16x16x32_bf16 v[52:55], v[68:71], v[216:219], v[52:55]
	v_mfma_f32_16x16x32_bf16 v[44:47], v[104:107], v[216:219], v[44:47]
	ds_read_b128 v[240:243], v199 offset:40960
	s_waitcnt lgkmcnt(4)
	v_mfma_f32_16x16x32_bf16 v[52:55], v[64:67], v[220:223], v[52:55]
	v_mfma_f32_16x16x32_bf16 v[44:47], v[96:99], v[220:223], v[44:47]
	ds_read_b128 v[244:247], v200 offset:40960
	s_waitcnt lgkmcnt(4)
	v_mfma_f32_16x16x32_bf16 v[168:171], v[40:43], v[228:231], v[52:55]
	v_mfma_f32_16x16x32_bf16 v[52:55], v[88:91], v[228:231], v[44:47]
	s_nop 3
	ds_read_b128 v[212:215], v201 offset:40960
	s_waitcnt lgkmcnt(4)
	v_mfma_f32_16x16x32_bf16 v[56:59], v[136:139], v[232:235], 0
	v_mfma_f32_16x16x32_bf16 v[44:47], v[152:155], v[232:235], 0
	ds_read_b128 v[216:219], v202 offset:40960
	s_waitcnt lgkmcnt(4)
	v_mfma_f32_16x16x32_bf16 v[56:59], v[120:123], v[236:239], v[56:59]
	v_mfma_f32_16x16x32_bf16 v[44:47], v[148:151], v[236:239], v[44:47]
	ds_read_b128 v[220:223], v203 offset:40960
	s_waitcnt lgkmcnt(4)
	v_mfma_f32_16x16x32_bf16 v[56:59], v[108:111], v[240:243], v[56:59]
	v_mfma_f32_16x16x32_bf16 v[44:47], v[144:147], v[240:243], v[44:47]
	ds_read_b128 v[228:231], v204 offset:40960
	s_waitcnt lgkmcnt(4)
	v_mfma_f32_16x16x32_bf16 v[56:59], v[100:103], v[244:247], v[56:59]
	v_mfma_f32_16x16x32_bf16 v[44:47], v[140:143], v[244:247], v[44:47]
	ds_read_b128 v[232:235], v184 offset:40960
	s_waitcnt lgkmcnt(4)
	v_mfma_f32_16x16x32_bf16 v[56:59], v[92:95], v[212:215], v[56:59]
	v_mfma_f32_16x16x32_bf16 v[44:47], v[132:135], v[212:215], v[44:47]
	ds_read_b128 v[236:239], v184 offset:41024
	s_waitcnt lgkmcnt(4)
	v_mfma_f32_16x16x32_bf16 v[56:59], v[84:87], v[216:219], v[56:59]
	v_mfma_f32_16x16x32_bf16 v[44:47], v[128:131], v[216:219], v[44:47]
	ds_read_b128 v[240:243], v184 offset:41088
	s_waitcnt lgkmcnt(4)
	v_mfma_f32_16x16x32_bf16 v[56:59], v[80:83], v[220:223], v[56:59]
	v_mfma_f32_16x16x32_bf16 v[44:47], v[124:127], v[220:223], v[44:47]
	ds_read_b128 v[244:247], v184 offset:41152
	s_waitcnt lgkmcnt(4)
	v_mfma_f32_16x16x32_bf16 v[56:59], v[76:79], v[228:231], v[56:59]
	v_mfma_f32_16x16x32_bf16 v[44:47], v[116:119], v[228:231], v[44:47]
	ds_read_b128 v[212:215], v197 offset:49152
	s_waitcnt lgkmcnt(4)
	v_mfma_f32_16x16x32_bf16 v[56:59], v[72:75], v[232:235], v[56:59]
	v_mfma_f32_16x16x32_bf16 v[44:47], v[112:115], v[232:235], v[44:47]
	ds_read_b128 v[216:219], v198 offset:49152
	s_waitcnt lgkmcnt(4)
	v_mfma_f32_16x16x32_bf16 v[56:59], v[68:71], v[236:239], v[56:59]
	v_mfma_f32_16x16x32_bf16 v[44:47], v[104:107], v[236:239], v[44:47]
	ds_read_b128 v[220:223], v199 offset:49152
	s_waitcnt lgkmcnt(4)
	v_mfma_f32_16x16x32_bf16 v[56:59], v[64:67], v[240:243], v[56:59]
	v_mfma_f32_16x16x32_bf16 v[44:47], v[96:99], v[240:243], v[44:47]
	ds_read_b128 v[228:231], v200 offset:49152
	s_waitcnt lgkmcnt(4)
	v_mfma_f32_16x16x32_bf16 v[176:179], v[40:43], v[244:247], v[56:59]
	v_mfma_f32_16x16x32_bf16 v[56:59], v[88:91], v[244:247], v[44:47]
	s_nop 3
	ds_read_b128 v[232:235], v201 offset:49152
	s_waitcnt lgkmcnt(4)
	v_mfma_f32_16x16x32_bf16 v[164:167], v[136:139], v[212:215], 0
	v_mfma_f32_16x16x32_bf16 v[44:47], v[152:155], v[212:215], 0
	ds_read_b128 v[236:239], v202 offset:49152
	s_waitcnt lgkmcnt(4)
	v_mfma_f32_16x16x32_bf16 v[164:167], v[120:123], v[216:219], v[164:167]
	v_mfma_f32_16x16x32_bf16 v[44:47], v[148:151], v[216:219], v[44:47]
	ds_read_b128 v[240:243], v203 offset:49152
	s_waitcnt lgkmcnt(4)
	v_mfma_f32_16x16x32_bf16 v[164:167], v[108:111], v[220:223], v[164:167]
	v_mfma_f32_16x16x32_bf16 v[44:47], v[144:147], v[220:223], v[44:47]
	ds_read_b128 v[244:247], v204 offset:49152
	s_waitcnt lgkmcnt(4)
	v_mfma_f32_16x16x32_bf16 v[164:167], v[100:103], v[228:231], v[164:167]
	v_mfma_f32_16x16x32_bf16 v[44:47], v[140:143], v[228:231], v[44:47]
	ds_read_b128 v[212:215], v184 offset:49152
	s_waitcnt lgkmcnt(4)
	v_mfma_f32_16x16x32_bf16 v[164:167], v[92:95], v[232:235], v[164:167]
	v_mfma_f32_16x16x32_bf16 v[44:47], v[132:135], v[232:235], v[44:47]
	ds_read_b128 v[216:219], v184 offset:49216
	s_waitcnt lgkmcnt(4)
	v_mfma_f32_16x16x32_bf16 v[164:167], v[84:87], v[236:239], v[164:167]
	v_mfma_f32_16x16x32_bf16 v[44:47], v[128:131], v[236:239], v[44:47]
	ds_read_b128 v[220:223], v184 offset:49280
	s_waitcnt lgkmcnt(4)
	v_mfma_f32_16x16x32_bf16 v[164:167], v[80:83], v[240:243], v[164:167]
	v_mfma_f32_16x16x32_bf16 v[44:47], v[124:127], v[240:243], v[44:47]
	ds_read_b128 v[228:231], v184 offset:49344
	s_waitcnt lgkmcnt(4)
	v_mfma_f32_16x16x32_bf16 v[164:167], v[76:79], v[244:247], v[164:167]
	v_mfma_f32_16x16x32_bf16 v[44:47], v[116:119], v[244:247], v[44:47]
	ds_read_b128 v[232:235], v197 offset:57344
	s_waitcnt lgkmcnt(4)
	v_mfma_f32_16x16x32_bf16 v[164:167], v[72:75], v[212:215], v[164:167]
	v_mfma_f32_16x16x32_bf16 v[44:47], v[112:115], v[212:215], v[44:47]
	ds_read_b128 v[236:239], v198 offset:57344
	s_waitcnt lgkmcnt(4)
	v_mfma_f32_16x16x32_bf16 v[164:167], v[68:71], v[216:219], v[164:167]
	v_mfma_f32_16x16x32_bf16 v[44:47], v[104:107], v[216:219], v[44:47]
	ds_read_b128 v[240:243], v199 offset:57344
	s_waitcnt lgkmcnt(4)
	v_mfma_f32_16x16x32_bf16 v[164:167], v[64:67], v[220:223], v[164:167]
	v_mfma_f32_16x16x32_bf16 v[44:47], v[96:99], v[220:223], v[44:47]
	ds_read_b128 v[244:247], v200 offset:57344
	s_waitcnt lgkmcnt(4)
	v_mfma_f32_16x16x32_bf16 v[164:167], v[40:43], v[228:231], v[164:167]
	v_mfma_f32_16x16x32_bf16 v[44:47], v[88:91], v[228:231], v[44:47]
	ds_read_b128 v[212:215], v201 offset:57344
	s_waitcnt lgkmcnt(4)
	v_mfma_f32_16x16x32_bf16 v[136:139], v[136:139], v[232:235], 0
	v_mfma_f32_16x16x32_bf16 v[152:155], v[152:155], v[232:235], 0
	ds_read_b128 v[216:219], v202 offset:57344
	s_waitcnt lgkmcnt(4)
	v_mfma_f32_16x16x32_bf16 v[120:123], v[120:123], v[236:239], v[136:139]
	v_mfma_f32_16x16x32_bf16 v[136:139], v[148:151], v[236:239], v[152:155]
	ds_read_b128 v[220:223], v203 offset:57344
	s_waitcnt lgkmcnt(4)
	v_mfma_f32_16x16x32_bf16 v[108:111], v[108:111], v[240:243], v[120:123]
	v_mfma_f32_16x16x32_bf16 v[120:123], v[144:147], v[240:243], v[136:139]
	s_nop 3
	ds_read_b128 v[228:231], v204 offset:57344
	s_waitcnt lgkmcnt(4)
	v_mfma_f32_16x16x32_bf16 v[100:103], v[100:103], v[244:247], v[108:111]
	v_mfma_f32_16x16x32_bf16 v[108:111], v[140:143], v[244:247], v[120:123]
	s_nop 2
	ds_read_b128 v[232:235], v184 offset:57344
	s_waitcnt lgkmcnt(4)
	v_mfma_f32_16x16x32_bf16 v[92:95], v[92:95], v[212:215], v[100:103]
	v_mfma_f32_16x16x32_bf16 v[100:103], v[132:135], v[212:215], v[108:111]
	s_nop 2
	ds_read_b128 v[236:239], v184 offset:57408
	s_waitcnt lgkmcnt(4)
	v_mfma_f32_16x16x32_bf16 v[84:87], v[84:87], v[216:219], v[92:95]
	v_mfma_f32_16x16x32_bf16 v[92:95], v[128:131], v[216:219], v[100:103]
	s_nop 2
	ds_read_b128 v[240:243], v184 offset:57472
	s_waitcnt lgkmcnt(4)
	v_mfma_f32_16x16x32_bf16 v[80:83], v[80:83], v[220:223], v[84:87]
	v_mfma_f32_16x16x32_bf16 v[84:87], v[124:127], v[220:223], v[92:95]
	s_nop 2
	ds_read_b128 v[244:247], v184 offset:57536
	s_waitcnt lgkmcnt(4)
	v_mfma_f32_16x16x32_bf16 v[76:79], v[76:79], v[228:231], v[80:83]
	v_mfma_f32_16x16x32_bf16 v[80:83], v[116:119], v[228:231], v[84:87]
	s_nop 2
	s_waitcnt lgkmcnt(3)
	v_mfma_f32_16x16x32_bf16 v[72:75], v[72:75], v[232:235], v[76:79]
	v_mfma_f32_16x16x32_bf16 v[76:79], v[112:115], v[232:235], v[80:83]
	s_nop 2
	s_waitcnt lgkmcnt(2)
	v_mfma_f32_16x16x32_bf16 v[68:71], v[68:71], v[236:239], v[72:75]
	v_mfma_f32_16x16x32_bf16 v[72:75], v[104:107], v[236:239], v[76:79]
	s_nop 2
	s_waitcnt lgkmcnt(1)
	v_mfma_f32_16x16x32_bf16 v[64:67], v[64:67], v[240:243], v[68:71]
	v_mfma_f32_16x16x32_bf16 v[68:71], v[96:99], v[240:243], v[72:75]
	s_nop 2
	s_waitcnt lgkmcnt(0)
	v_mfma_f32_16x16x32_bf16 v[64:67], v[40:43], v[244:247], v[64:67]
	s_barrier
	v_mfma_f32_16x16x32_bf16 v[40:43], v[88:91], v[244:247], v[68:71]
	s_nop 2
	v_mov_b32_e32 v80, 0xbdd2d3e8
	v_mov_b32_e32 v81, 0xbdd2d3e8
	v_mov_b32_e32 v82, 0xc0135761
	v_mov_b32_e32 v83, 0xc0135761
	v_mov_b32_e32 v84, 1.0
	v_mov_b32_e32 v85, 1.0
	v_pk_mul_f32 v[76:77], v[156:157], v[156:157]
	v_pk_mul_f32 v[78:79], v[158:159], v[158:159]
	v_pk_fma_f32 v[76:77], v[76:77], v[80:81], v[82:83]
	v_pk_fma_f32 v[78:79], v[78:79], v[80:81], v[82:83]
	v_pk_mul_f32 v[76:77], v[156:157], v[76:77]
	v_pk_mul_f32 v[78:79], v[158:159], v[78:79]
	v_exp_f32_e32 v76, v76
	v_exp_f32_e32 v77, v77
	v_exp_f32_e32 v78, v78
	v_exp_f32_e32 v79, v79
	v_pk_add_f32 v[76:77], v[76:77], v[84:85]
	v_pk_add_f32 v[78:79], v[78:79], v[84:85]
	v_rcp_f32_e32 v76, v76
	v_rcp_f32_e32 v77, v77
	v_rcp_f32_e32 v78, v78
	v_rcp_f32_e32 v79, v79
	v_pk_mul_f32 v[76:77], v[156:157], v[76:77]
	v_pk_mul_f32 v[78:79], v[158:159], v[78:79]
	v_cvt_pk_bf16_f32 v70, v76, v77
	v_cvt_pk_bf16_f32 v71, v78, v79
	v_add_u32_e32 v68, s50, v196
	v_add3_u32 v68, 0, v205, v68
	v_mbcnt_lo_u32_b32 v94, -1, 0
	v_mbcnt_hi_u32_b32 v94, -1, v94
	v_and_b32_e32 v94, 7, v94
	v_lshlrev_b32_e32 v94, 4, v94
	v_or_b32_e32 v95, 32, v68
	v_xor_b32_e32 v68, v94, v68
	v_xor_b32_e32 v95, v94, v95
	ds_write_b64 v68, v[70:71]
	v_pk_mul_f32 v[86:87], v[172:173], v[172:173]
	v_pk_mul_f32 v[92:93], v[174:175], v[174:175]
	v_pk_fma_f32 v[86:87], v[86:87], v[80:81], v[82:83]
	v_pk_fma_f32 v[92:93], v[92:93], v[80:81], v[82:83]
	v_pk_mul_f32 v[86:87], v[172:173], v[86:87]
	v_pk_mul_f32 v[92:93], v[174:175], v[92:93]
	v_exp_f32_e32 v86, v86
	v_exp_f32_e32 v87, v87
	v_exp_f32_e32 v92, v92
	v_exp_f32_e32 v93, v93
	v_pk_add_f32 v[86:87], v[86:87], v[84:85]
	v_pk_add_f32 v[92:93], v[92:93], v[84:85]
	v_rcp_f32_e32 v86, v86
	v_rcp_f32_e32 v87, v87
	v_rcp_f32_e32 v92, v92
	v_rcp_f32_e32 v93, v93
	v_pk_mul_f32 v[86:87], v[172:173], v[86:87]
	v_pk_mul_f32 v[92:93], v[174:175], v[92:93]
	v_cvt_pk_bf16_f32 v70, v86, v87
	v_cvt_pk_bf16_f32 v71, v92, v93
	ds_write_b64 v68, v[70:71] offset:8192
	v_pk_mul_f32 v[76:77], v[160:161], v[160:161]
	v_pk_mul_f32 v[78:79], v[162:163], v[162:163]
	v_pk_fma_f32 v[76:77], v[76:77], v[80:81], v[82:83]
	v_pk_fma_f32 v[78:79], v[78:79], v[80:81], v[82:83]
	v_pk_mul_f32 v[76:77], v[160:161], v[76:77]
	v_pk_mul_f32 v[78:79], v[162:163], v[78:79]
	v_exp_f32_e32 v76, v76
	v_exp_f32_e32 v77, v77
	v_exp_f32_e32 v78, v78
	v_exp_f32_e32 v79, v79
	v_pk_add_f32 v[76:77], v[76:77], v[84:85]
	v_pk_add_f32 v[78:79], v[78:79], v[84:85]
	v_rcp_f32_e32 v76, v76
	v_rcp_f32_e32 v77, v77
	v_rcp_f32_e32 v78, v78
	v_rcp_f32_e32 v79, v79
	v_pk_mul_f32 v[76:77], v[160:161], v[76:77]
	v_pk_mul_f32 v[78:79], v[162:163], v[78:79]
	v_cvt_pk_bf16_f32 v70, v76, v77
	v_cvt_pk_bf16_f32 v71, v78, v79
	ds_write_b64 v68, v[70:71] offset:16384
	v_pk_mul_f32 v[86:87], v[180:181], v[180:181]
	v_pk_mul_f32 v[92:93], v[182:183], v[182:183]
	v_pk_fma_f32 v[86:87], v[86:87], v[80:81], v[82:83]
	v_pk_fma_f32 v[92:93], v[92:93], v[80:81], v[82:83]
	v_pk_mul_f32 v[86:87], v[180:181], v[86:87]
	v_pk_mul_f32 v[92:93], v[182:183], v[92:93]
	v_exp_f32_e32 v86, v86
	v_exp_f32_e32 v87, v87
	v_exp_f32_e32 v92, v92
	v_exp_f32_e32 v93, v93
	v_pk_add_f32 v[86:87], v[86:87], v[84:85]
	v_pk_add_f32 v[92:93], v[92:93], v[84:85]
	v_rcp_f32_e32 v86, v86
	v_rcp_f32_e32 v87, v87
	v_rcp_f32_e32 v92, v92
	v_rcp_f32_e32 v93, v93
	v_pk_mul_f32 v[86:87], v[180:181], v[86:87]
	v_pk_mul_f32 v[92:93], v[182:183], v[92:93]
	v_cvt_pk_bf16_f32 v70, v86, v87
	v_cvt_pk_bf16_f32 v71, v92, v93
	ds_write_b64 v68, v[70:71] offset:24576
	v_pk_mul_f32 v[76:77], v[168:169], v[168:169]
	v_pk_mul_f32 v[78:79], v[170:171], v[170:171]
	v_pk_fma_f32 v[76:77], v[76:77], v[80:81], v[82:83]
	v_pk_fma_f32 v[78:79], v[78:79], v[80:81], v[82:83]
	v_pk_mul_f32 v[76:77], v[168:169], v[76:77]
	v_pk_mul_f32 v[78:79], v[170:171], v[78:79]
	v_exp_f32_e32 v76, v76
	v_exp_f32_e32 v77, v77
	v_exp_f32_e32 v78, v78
	v_exp_f32_e32 v79, v79
	v_pk_add_f32 v[76:77], v[76:77], v[84:85]
	v_pk_add_f32 v[78:79], v[78:79], v[84:85]
	v_rcp_f32_e32 v76, v76
	v_rcp_f32_e32 v77, v77
	v_rcp_f32_e32 v78, v78
	v_rcp_f32_e32 v79, v79
	v_pk_mul_f32 v[76:77], v[168:169], v[76:77]
	v_pk_mul_f32 v[78:79], v[170:171], v[78:79]
	v_cvt_pk_bf16_f32 v70, v76, v77
	v_cvt_pk_bf16_f32 v71, v78, v79
	ds_write_b64 v68, v[70:71] offset:32768
	v_pk_mul_f32 v[86:87], v[176:177], v[176:177]
	v_pk_mul_f32 v[92:93], v[178:179], v[178:179]
	v_pk_fma_f32 v[86:87], v[86:87], v[80:81], v[82:83]
	v_pk_fma_f32 v[92:93], v[92:93], v[80:81], v[82:83]
	v_pk_mul_f32 v[86:87], v[176:177], v[86:87]
	v_pk_mul_f32 v[92:93], v[178:179], v[92:93]
	v_exp_f32_e32 v86, v86
	v_exp_f32_e32 v87, v87
	v_exp_f32_e32 v92, v92
	v_exp_f32_e32 v93, v93
	v_pk_add_f32 v[86:87], v[86:87], v[84:85]
	v_pk_add_f32 v[92:93], v[92:93], v[84:85]
	v_rcp_f32_e32 v86, v86
	v_rcp_f32_e32 v87, v87
	v_rcp_f32_e32 v92, v92
	v_rcp_f32_e32 v93, v93
	v_pk_mul_f32 v[86:87], v[176:177], v[86:87]
	v_pk_mul_f32 v[92:93], v[178:179], v[92:93]
	v_cvt_pk_bf16_f32 v70, v86, v87
	v_cvt_pk_bf16_f32 v71, v92, v93
	ds_write_b64 v68, v[70:71] offset:40960
	v_pk_mul_f32 v[76:77], v[164:165], v[164:165]
	v_pk_mul_f32 v[78:79], v[166:167], v[166:167]
	v_pk_fma_f32 v[76:77], v[76:77], v[80:81], v[82:83]
	v_pk_fma_f32 v[78:79], v[78:79], v[80:81], v[82:83]
	v_pk_mul_f32 v[76:77], v[164:165], v[76:77]
	v_pk_mul_f32 v[78:79], v[166:167], v[78:79]
	v_exp_f32_e32 v76, v76
	v_exp_f32_e32 v77, v77
	v_exp_f32_e32 v78, v78
	v_exp_f32_e32 v79, v79
	v_pk_add_f32 v[76:77], v[76:77], v[84:85]
	v_pk_add_f32 v[78:79], v[78:79], v[84:85]
	v_rcp_f32_e32 v76, v76
	v_rcp_f32_e32 v77, v77
	v_rcp_f32_e32 v78, v78
	v_rcp_f32_e32 v79, v79
	v_pk_mul_f32 v[76:77], v[164:165], v[76:77]
	v_pk_mul_f32 v[78:79], v[166:167], v[78:79]
	v_cvt_pk_bf16_f32 v70, v76, v77
	v_cvt_pk_bf16_f32 v71, v78, v79
	ds_write_b64 v68, v[70:71] offset:49152
	s_nop 0
	v_pk_mul_f32 v[86:87], v[64:65], v[64:65]
	v_pk_mul_f32 v[92:93], v[66:67], v[66:67]
	v_pk_fma_f32 v[86:87], v[86:87], v[80:81], v[82:83]
	v_pk_fma_f32 v[92:93], v[92:93], v[80:81], v[82:83]
	v_pk_mul_f32 v[86:87], v[64:65], v[86:87]
	v_pk_mul_f32 v[92:93], v[66:67], v[92:93]
	v_exp_f32_e32 v86, v86
	v_exp_f32_e32 v87, v87
	v_exp_f32_e32 v92, v92
	v_exp_f32_e32 v93, v93
	v_pk_add_f32 v[86:87], v[86:87], v[84:85]
	v_pk_add_f32 v[92:93], v[92:93], v[84:85]
	v_rcp_f32_e32 v86, v86
	v_rcp_f32_e32 v87, v87
	v_rcp_f32_e32 v92, v92
	v_rcp_f32_e32 v93, v93
	v_pk_mul_f32 v[86:87], v[64:65], v[86:87]
	v_pk_mul_f32 v[92:93], v[66:67], v[92:93]
	s_nop 0
	s_nop 0
	v_cvt_pk_bf16_f32 v64, v86, v87
	s_nop 0
	s_nop 0
	s_nop 0
	s_nop 0
	v_cvt_pk_bf16_f32 v65, v92, v93
	ds_write_b64 v68, v[64:65] offset:57344
	s_nop 0
	s_nop 0
	v_pk_mul_f32 v[76:77], v[32:33], v[32:33]
	v_pk_mul_f32 v[78:79], v[34:35], v[34:35]
	v_pk_fma_f32 v[76:77], v[76:77], v[80:81], v[82:83]
	v_pk_fma_f32 v[78:79], v[78:79], v[80:81], v[82:83]
	v_pk_mul_f32 v[76:77], v[32:33], v[76:77]
	v_pk_mul_f32 v[78:79], v[34:35], v[78:79]
	v_exp_f32_e32 v76, v76
	v_exp_f32_e32 v77, v77
	v_exp_f32_e32 v78, v78
	v_exp_f32_e32 v79, v79
	v_pk_add_f32 v[76:77], v[76:77], v[84:85]
	v_pk_add_f32 v[78:79], v[78:79], v[84:85]
	v_rcp_f32_e32 v76, v76
	v_rcp_f32_e32 v77, v77
	v_rcp_f32_e32 v78, v78
	v_rcp_f32_e32 v79, v79
	v_pk_mul_f32 v[76:77], v[32:33], v[76:77]
	v_pk_mul_f32 v[78:79], v[34:35], v[78:79]
	s_nop 0
	s_nop 0
	v_cvt_pk_bf16_f32 v32, v76, v77
	s_nop 0
	s_nop 0
	s_nop 0
	s_nop 0
	v_cvt_pk_bf16_f32 v33, v78, v79
	ds_write_b64 v95, v[32:33]
	v_pk_mul_f32 v[86:87], v[48:49], v[48:49]
	v_pk_mul_f32 v[92:93], v[50:51], v[50:51]
	v_pk_fma_f32 v[86:87], v[86:87], v[80:81], v[82:83]
	v_pk_fma_f32 v[92:93], v[92:93], v[80:81], v[82:83]
	v_pk_mul_f32 v[86:87], v[48:49], v[86:87]
	v_pk_mul_f32 v[92:93], v[50:51], v[92:93]
	v_exp_f32_e32 v86, v86
	v_exp_f32_e32 v87, v87
	v_exp_f32_e32 v92, v92
	v_exp_f32_e32 v93, v93
	v_pk_add_f32 v[86:87], v[86:87], v[84:85]
	v_pk_add_f32 v[92:93], v[92:93], v[84:85]
	v_rcp_f32_e32 v86, v86
	v_rcp_f32_e32 v87, v87
	v_rcp_f32_e32 v92, v92
	v_rcp_f32_e32 v93, v93
	v_pk_mul_f32 v[86:87], v[48:49], v[86:87]
	v_pk_mul_f32 v[92:93], v[50:51], v[92:93]
	v_cvt_pk_bf16_f32 v32, v86, v87
	v_cvt_pk_bf16_f32 v33, v92, v93
	ds_write_b64 v95, v[32:33] offset:8192
	v_pk_mul_f32 v[76:77], v[36:37], v[36:37]
	v_pk_mul_f32 v[78:79], v[38:39], v[38:39]
	v_pk_fma_f32 v[76:77], v[76:77], v[80:81], v[82:83]
	v_pk_fma_f32 v[78:79], v[78:79], v[80:81], v[82:83]
	v_pk_mul_f32 v[76:77], v[36:37], v[76:77]
	v_pk_mul_f32 v[78:79], v[38:39], v[78:79]
	v_exp_f32_e32 v76, v76
	v_exp_f32_e32 v77, v77
	v_exp_f32_e32 v78, v78
	v_exp_f32_e32 v79, v79
	v_pk_add_f32 v[76:77], v[76:77], v[84:85]
	v_pk_add_f32 v[78:79], v[78:79], v[84:85]
	v_rcp_f32_e32 v76, v76
	v_rcp_f32_e32 v77, v77
	v_rcp_f32_e32 v78, v78
	v_rcp_f32_e32 v79, v79
	v_pk_mul_f32 v[76:77], v[36:37], v[76:77]
	v_pk_mul_f32 v[78:79], v[38:39], v[78:79]
	v_cvt_pk_bf16_f32 v32, v76, v77
	v_lshl_add_u64 v[36:37], v[186:187], 4, s[22:23]
	v_add_co_u32_e32 v38, vcc, s25, v36
	v_cvt_pk_bf16_f32 v33, v78, v79
	ds_write_b64 v95, v[32:33] offset:16384
	v_pk_mul_f32 v[86:87], v[60:61], v[60:61]
	v_pk_mul_f32 v[92:93], v[62:63], v[62:63]
	v_pk_fma_f32 v[86:87], v[86:87], v[80:81], v[82:83]
	v_pk_fma_f32 v[92:93], v[92:93], v[80:81], v[82:83]
	v_pk_mul_f32 v[86:87], v[60:61], v[86:87]
	v_pk_mul_f32 v[92:93], v[62:63], v[92:93]
	v_exp_f32_e32 v86, v86
	v_exp_f32_e32 v87, v87
	v_exp_f32_e32 v92, v92
	v_exp_f32_e32 v93, v93
	v_pk_add_f32 v[86:87], v[86:87], v[84:85]
	v_pk_add_f32 v[92:93], v[92:93], v[84:85]
	v_rcp_f32_e32 v86, v86
	v_rcp_f32_e32 v87, v87
	v_rcp_f32_e32 v92, v92
	v_rcp_f32_e32 v93, v93
	v_pk_mul_f32 v[86:87], v[60:61], v[86:87]
	v_pk_mul_f32 v[92:93], v[62:63], v[92:93]
	v_cvt_pk_bf16_f32 v32, v86, v87
	v_addc_co_u32_e32 v39, vcc, 0, v37, vcc
	v_cvt_pk_bf16_f32 v33, v92, v93
	ds_write_b64 v95, v[32:33] offset:24576
	v_pk_mul_f32 v[76:77], v[52:53], v[52:53]
	v_pk_mul_f32 v[78:79], v[54:55], v[54:55]
	v_pk_fma_f32 v[76:77], v[76:77], v[80:81], v[82:83]
	v_pk_fma_f32 v[78:79], v[78:79], v[80:81], v[82:83]
	v_pk_mul_f32 v[76:77], v[52:53], v[76:77]
	v_pk_mul_f32 v[78:79], v[54:55], v[78:79]
	v_exp_f32_e32 v76, v76
	v_exp_f32_e32 v77, v77
	v_exp_f32_e32 v78, v78
	v_exp_f32_e32 v79, v79
	v_pk_add_f32 v[76:77], v[76:77], v[84:85]
	v_pk_add_f32 v[78:79], v[78:79], v[84:85]
	v_rcp_f32_e32 v76, v76
	v_rcp_f32_e32 v77, v77
	v_rcp_f32_e32 v78, v78
	v_rcp_f32_e32 v79, v79
	v_pk_mul_f32 v[76:77], v[52:53], v[76:77]
	v_pk_mul_f32 v[78:79], v[54:55], v[78:79]
	v_cvt_pk_bf16_f32 v32, v76, v77
	v_cvt_pk_bf16_f32 v33, v78, v79
	ds_write_b64 v95, v[32:33] offset:32768
	v_pk_mul_f32 v[86:87], v[56:57], v[56:57]
	v_pk_mul_f32 v[92:93], v[58:59], v[58:59]
	v_pk_fma_f32 v[86:87], v[86:87], v[80:81], v[82:83]
	v_pk_fma_f32 v[92:93], v[92:93], v[80:81], v[82:83]
	v_pk_mul_f32 v[86:87], v[56:57], v[86:87]
	v_pk_mul_f32 v[92:93], v[58:59], v[92:93]
	v_exp_f32_e32 v86, v86
	v_exp_f32_e32 v87, v87
	v_exp_f32_e32 v92, v92
	v_exp_f32_e32 v93, v93
	v_pk_add_f32 v[86:87], v[86:87], v[84:85]
	v_pk_add_f32 v[92:93], v[92:93], v[84:85]
	v_rcp_f32_e32 v86, v86
	v_rcp_f32_e32 v87, v87
	v_rcp_f32_e32 v92, v92
	v_rcp_f32_e32 v93, v93
	v_pk_mul_f32 v[86:87], v[56:57], v[86:87]
	v_pk_mul_f32 v[92:93], v[58:59], v[92:93]
	v_cvt_pk_bf16_f32 v32, v86, v87
	v_cvt_pk_bf16_f32 v33, v92, v93
	ds_write_b64 v95, v[32:33] offset:40960
	v_pk_mul_f32 v[76:77], v[44:45], v[44:45]
	v_pk_mul_f32 v[78:79], v[46:47], v[46:47]
	v_pk_fma_f32 v[76:77], v[76:77], v[80:81], v[82:83]
	v_pk_fma_f32 v[78:79], v[78:79], v[80:81], v[82:83]
	v_pk_mul_f32 v[76:77], v[44:45], v[76:77]
	v_pk_mul_f32 v[78:79], v[46:47], v[78:79]
	v_exp_f32_e32 v76, v76
	v_exp_f32_e32 v77, v77
	v_exp_f32_e32 v78, v78
	v_exp_f32_e32 v79, v79
	v_pk_add_f32 v[76:77], v[76:77], v[84:85]
	v_pk_add_f32 v[78:79], v[78:79], v[84:85]
	v_rcp_f32_e32 v76, v76
	v_rcp_f32_e32 v77, v77
	v_rcp_f32_e32 v78, v78
	v_rcp_f32_e32 v79, v79
	v_pk_mul_f32 v[76:77], v[44:45], v[76:77]
	v_pk_mul_f32 v[78:79], v[46:47], v[78:79]
	v_cvt_pk_bf16_f32 v32, v76, v77
	v_cvt_pk_bf16_f32 v33, v78, v79
	ds_write_b64 v95, v[32:33] offset:49152
	v_pk_mul_f32 v[86:87], v[40:41], v[40:41]
	v_pk_mul_f32 v[92:93], v[42:43], v[42:43]
	v_pk_fma_f32 v[86:87], v[86:87], v[80:81], v[82:83]
	v_pk_fma_f32 v[92:93], v[92:93], v[80:81], v[82:83]
	v_pk_mul_f32 v[86:87], v[40:41], v[86:87]
	v_pk_mul_f32 v[92:93], v[42:43], v[92:93]
	v_exp_f32_e32 v86, v86
	v_exp_f32_e32 v87, v87
	v_exp_f32_e32 v92, v92
	v_exp_f32_e32 v93, v93
	v_pk_add_f32 v[86:87], v[86:87], v[84:85]
	v_pk_add_f32 v[92:93], v[92:93], v[84:85]
	v_rcp_f32_e32 v86, v86
	v_rcp_f32_e32 v87, v87
	v_rcp_f32_e32 v92, v92
	v_rcp_f32_e32 v93, v93
	v_pk_mul_f32 v[86:87], v[40:41], v[86:87]
	v_pk_mul_f32 v[92:93], v[42:43], v[92:93]
	v_cvt_pk_bf16_f32 v32, v86, v87
	v_cvt_pk_bf16_f32 v33, v92, v93
	ds_write_b64 v95, v[32:33] offset:57344
	v_lshl_add_u32 v32, v186, 4, 0
	v_lshrrev_b32_e32 v94, 1, v186
	v_and_b32_e32 v94, 0x70, v94
	v_xor_b32_e32 v32, v94, v32
	s_waitcnt lgkmcnt(0)
	s_barrier
	ds_read_b128 v[32:35], v32
	s_waitcnt lgkmcnt(0)
	global_store_dwordx4 v[36:37], v[32:35], off
	s_nop 1
	v_lshl_add_u32 v32, v189, 4, 0
	v_lshrrev_b32_e32 v94, 1, v189
	v_and_b32_e32 v94, 0x70, v94
	v_xor_b32_e32 v32, v94, v32
	ds_read_b128 v[32:35], v32
	s_waitcnt lgkmcnt(0)
	global_store_dwordx4 v[38:39], v[32:35], off
	s_nop 1
	v_lshl_add_u32 v32, v190, 4, 0
	v_lshrrev_b32_e32 v94, 1, v190
	v_and_b32_e32 v94, 0x70, v94
	v_xor_b32_e32 v32, v94, v32
	ds_read_b128 v[32:35], v32
	v_add_co_u32_e32 v38, vcc, s36, v36
	s_nop 1
	v_addc_co_u32_e32 v39, vcc, 0, v37, vcc
	s_waitcnt lgkmcnt(0)
	global_store_dwordx4 v[38:39], v[32:35], off
	v_add_co_u32_e32 v38, vcc, s37, v36
	s_nop 0
	v_lshl_add_u32 v32, v191, 4, 0
	v_lshrrev_b32_e32 v94, 1, v191
	v_and_b32_e32 v94, 0x70, v94
	v_xor_b32_e32 v32, v94, v32
	ds_read_b128 v[32:35], v32
	v_addc_co_u32_e32 v39, vcc, 0, v37, vcc
	s_waitcnt lgkmcnt(0)
	global_store_dwordx4 v[38:39], v[32:35], off
	s_nop 1
	v_lshl_add_u32 v32, v192, 4, 0
	v_lshrrev_b32_e32 v94, 1, v192
	v_and_b32_e32 v94, 0x70, v94
	v_xor_b32_e32 v32, v94, v32
	ds_read_b128 v[32:35], v32
	v_add_co_u32_e32 v38, vcc, s38, v36
	s_nop 1
	v_addc_co_u32_e32 v39, vcc, 0, v37, vcc
	s_waitcnt lgkmcnt(0)
	global_store_dwordx4 v[38:39], v[32:35], off
	v_add_co_u32_e32 v38, vcc, s39, v36
	s_nop 0
	v_lshl_add_u32 v32, v193, 4, 0
	v_lshrrev_b32_e32 v94, 1, v193
	v_and_b32_e32 v94, 0x70, v94
	v_xor_b32_e32 v32, v94, v32
	ds_read_b128 v[32:35], v32
	v_addc_co_u32_e32 v39, vcc, 0, v37, vcc
	s_waitcnt lgkmcnt(0)
	global_store_dwordx4 v[38:39], v[32:35], off
	s_nop 1
	v_lshl_add_u32 v32, v194, 4, 0
	v_lshrrev_b32_e32 v94, 1, v194
	v_and_b32_e32 v94, 0x70, v94
	v_xor_b32_e32 v32, v94, v32
	ds_read_b128 v[32:35], v32
	v_add_co_u32_e32 v38, vcc, 0xc000, v36
	s_nop 1
	v_addc_co_u32_e32 v39, vcc, 0, v37, vcc
	s_waitcnt lgkmcnt(0)
	global_store_dwordx4 v[38:39], v[32:35], off
	v_add_co_u32_e32 v36, vcc, 0xe000, v36
	s_nop 0
	v_lshl_add_u32 v32, v195, 4, 0
	v_lshrrev_b32_e32 v94, 1, v195
	v_and_b32_e32 v94, 0x70, v94
	v_xor_b32_e32 v32, v94, v32
	ds_read_b128 v[32:35], v32
	v_addc_co_u32_e32 v37, vcc, 0, v37, vcc
	s_and_b64 vcc, exec, s[6:7]
	s_waitcnt lgkmcnt(0)
	global_store_dwordx4 v[36:37], v[32:35], off
	s_barrier
	s_cbranch_vccnz .LBB0_503
.LBB0_496:
	s_add_i32 s44, s51, s84
	s_cmpk_gt_i32 s44, 0x1ff
	v_mbcnt_lo_u32_b32 v157, -1, 0
	v_mbcnt_hi_u32_b32 v157, -1, v157
	s_cselect_b64 s[6:7], -1, 0
	v_add_u32_e32 v186, s33, v157
	s_and_b32 s45, s51, 31
	s_ashr_i32 s0, s44, 5
	s_cmpk_lt_i32 s44, 0x200
	v_readfirstlane_b32 s23, v186
	s_cselect_b32 s0, s0, -1
	s_ashr_i32 s22, s23, 6
	v_and_b32_e32 v182, 15, v157
	s_lshl_b32 s26, s45, 17
	v_lshl_or_b32 v32, s22, 4, v182
	s_add_u32 s26, s92, s26
	v_ashrrev_i32_e32 v33, 31, v32
	s_addc_u32 s27, s93, 0
	v_lshlrev_b64 v[32:33], 9, v[32:33]
	v_lshl_add_u64 v[32:33], s[26:27], 0, v[32:33]
	v_and_b32_e32 v184, 48, v157
	v_lshl_add_u64 v[32:33], v[32:33], 0, v[184:185]
	global_load_dwordx4 v[48:51], v[32:33], off
	global_load_dwordx4 v[52:55], v[32:33], off offset:64
	global_load_dwordx4 v[56:59], v[32:33], off offset:128
	global_load_dwordx4 v[60:63], v[32:33], off offset:192
	global_load_dwordx4 v[44:47], v[32:33], off offset:256
	global_load_dwordx4 v[40:43], v[32:33], off offset:320
	global_load_dwordx4 v[36:39], v[32:33], off offset:384
	s_nop 0
	global_load_dwordx4 v[32:35], v[32:33], off offset:448
	v_and_b32_e32 v64, 31, v157
	v_ashrrev_i32_e32 v65, 5, v186
	v_lshlrev_b32_e32 v66, 9, v65
	v_bitop3_b32 v65, v65, v64, 15 bitop3:0x6c
	v_lshlrev_b32_e32 v65, 4, v65
	v_add3_u32 v65, 0, v66, v65
	v_add_u32_e32 v189, 0x200, v186
	s_waitcnt vmcnt(15)
	ds_write_b128 v65, v[0:3]
	v_ashrrev_i32_e32 v65, 5, v189
	v_lshlrev_b32_e32 v66, 9, v65
	v_bitop3_b32 v65, v65, v64, 15 bitop3:0x6c
	v_lshlrev_b32_e32 v65, 4, v65
	v_add3_u32 v65, 0, v66, v65
	v_add_u32_e32 v190, 0x400, v186
	s_waitcnt vmcnt(14)
	ds_write_b128 v65, v[4:7]
	v_ashrrev_i32_e32 v65, 5, v190
	v_lshlrev_b32_e32 v66, 9, v65
	v_bitop3_b32 v65, v65, v64, 15 bitop3:0x6c
	v_lshlrev_b32_e32 v65, 4, v65
	v_add3_u32 v65, 0, v66, v65
	v_add_u32_e32 v191, 0x600, v186
	s_waitcnt vmcnt(13)
	ds_write_b128 v65, v[8:11]
	v_ashrrev_i32_e32 v65, 5, v191
	v_lshlrev_b32_e32 v66, 9, v65
	v_bitop3_b32 v65, v65, v64, 15 bitop3:0x6c
	v_lshlrev_b32_e32 v65, 4, v65
	v_add3_u32 v65, 0, v66, v65
	v_add_u32_e32 v192, 0x800, v186
	s_waitcnt vmcnt(12)
	ds_write_b128 v65, v[12:15]
	v_ashrrev_i32_e32 v65, 5, v192
	v_lshlrev_b32_e32 v66, 9, v65
	v_bitop3_b32 v65, v65, v64, 15 bitop3:0x6c
	v_lshlrev_b32_e32 v65, 4, v65
	v_add3_u32 v65, 0, v66, v65
	v_add_u32_e32 v193, 0xa00, v186
	s_waitcnt vmcnt(11)
	ds_write_b128 v65, v[16:19]
	v_ashrrev_i32_e32 v65, 5, v193
	v_lshlrev_b32_e32 v66, 9, v65
	v_bitop3_b32 v65, v65, v64, 15 bitop3:0x6c
	v_lshlrev_b32_e32 v65, 4, v65
	v_add3_u32 v65, 0, v66, v65
	v_add_u32_e32 v194, 0xc00, v186
	s_waitcnt vmcnt(10)
	ds_write_b128 v65, v[20:23]
	v_ashrrev_i32_e32 v65, 5, v194
	v_lshlrev_b32_e32 v66, 9, v65
	v_bitop3_b32 v65, v65, v64, 15 bitop3:0x6c
	v_lshlrev_b32_e32 v65, 4, v65
	v_add3_u32 v65, 0, v66, v65
	v_add_u32_e32 v195, 0xe00, v186
	s_waitcnt vmcnt(9)
	ds_write_b128 v65, v[24:27]
	v_ashrrev_i32_e32 v65, 5, v195
	v_bitop3_b32 v64, v65, v64, 15 bitop3:0x6c
	v_lshlrev_b32_e32 v66, 9, v65
	v_lshlrev_b32_e32 v64, 4, v64
	v_bfe_u32 v156, v157, 4, 2
	v_add3_u32 v64, 0, v66, v64
	s_waitcnt vmcnt(8)
	ds_write_b128 v64, v[28:31]
	v_lshlrev_b32_e32 v196, 9, v182
	v_bitop3_b32 v64, v156, v157, 15 bitop3:0x78
	v_add_u32_e32 v100, 0, v196
	v_lshlrev_b32_e32 v64, 4, v64
	v_add_u32_e32 v197, v100, v64
	s_waitcnt lgkmcnt(0)
	s_barrier
	ds_read_b128 v[216:219], v197
	v_bitop3_b32 v72, v156, v182, 4 bitop3:0x36
	v_lshlrev_b32_e32 v72, 4, v72
	v_add_u32_e32 v198, v100, v72
	v_bitop3_b32 v72, v156, v182, 8 bitop3:0x36
	v_lshlrev_b32_e32 v72, 4, v72
	v_add_u32_e32 v199, v100, v72
	v_bitop3_b32 v72, v156, v182, 12 bitop3:0x36
	v_lshlrev_b32_e32 v72, 4, v72
	v_add_u32_e32 v200, v100, v72
	v_bitop3_b32 v72, v156, v182, 16 bitop3:0x36
	v_lshlrev_b32_e32 v72, 4, v72
	v_add_u32_e32 v201, v100, v72
	v_bitop3_b32 v72, v156, v182, 20 bitop3:0x36
	v_lshlrev_b32_e32 v72, 4, v72
	v_add_u32_e32 v202, v100, v72
	v_bitop3_b32 v72, v156, v182, 24 bitop3:0x36
	v_lshlrev_b32_e32 v72, 4, v72
	v_add_u32_e32 v203, v100, v72
	v_bitop3_b32 v72, v156, v182, 28 bitop3:0x36
	v_lshlrev_b32_e32 v72, 4, v72
	v_add_u32_e32 v204, v100, v72
	s_waitcnt vmcnt(7)
	ds_read_b128 v[220:223], v198
	ds_read_b128 v[228:231], v199
	ds_read_b128 v[232:235], v200
	ds_read_b128 v[236:239], v201
	s_waitcnt lgkmcnt(4)
	v_mfma_f32_16x16x32_bf16 v[64:67], v[216:219], v[48:51], 0
	s_and_b32 s50, s23, 0xffffffc0
	s_add_i32 s26, s50, 0
	s_waitcnt vmcnt(6)
	ds_read_b128 v[240:243], v202
	s_waitcnt lgkmcnt(4)
	v_mfma_f32_16x16x32_bf16 v[64:67], v[220:223], v[52:55], v[64:67]
	s_waitcnt vmcnt(5)
	ds_read_b128 v[244:247], v203
	s_waitcnt lgkmcnt(4)
	v_mfma_f32_16x16x32_bf16 v[64:67], v[228:231], v[56:59], v[64:67]
	s_waitcnt vmcnt(4)
	ds_read_b128 v[248:251], v204
	s_waitcnt lgkmcnt(4)
	v_mfma_f32_16x16x32_bf16 v[64:67], v[232:235], v[60:63], v[64:67]
	s_waitcnt vmcnt(3)
	ds_read_b128 v[216:219], v197 offset:8192
	s_waitcnt lgkmcnt(4)
	v_mfma_f32_16x16x32_bf16 v[64:67], v[236:239], v[44:47], v[64:67]
	s_waitcnt vmcnt(2)
	ds_read_b128 v[220:223], v198 offset:8192
	s_waitcnt lgkmcnt(4)
	v_mfma_f32_16x16x32_bf16 v[64:67], v[240:243], v[40:43], v[64:67]
	s_waitcnt vmcnt(1)
	ds_read_b128 v[228:231], v199 offset:8192
	s_waitcnt lgkmcnt(4)
	v_mfma_f32_16x16x32_bf16 v[64:67], v[244:247], v[36:39], v[64:67]
	s_waitcnt vmcnt(0)
	ds_read_b128 v[232:235], v200 offset:8192
	s_waitcnt lgkmcnt(4)
	v_mfma_f32_16x16x32_bf16 v[158:161], v[248:251], v[32:35], v[64:67]
	s_add_i32 s52, s26, 0x10000
	s_mul_i32 s26, s45, 0x30000
	s_add_u32 s26, s5, s26
	ds_read_b128 v[236:239], v201 offset:8192
	s_waitcnt lgkmcnt(4)
	v_mfma_f32_16x16x32_bf16 v[64:67], v[216:219], v[48:51], 0
	s_addc_u32 s27, s24, 0
	s_cmp_lt_i32 s0, 0
	v_ashrrev_i32_e32 v187, 31, v186
	ds_read_b128 v[240:243], v202 offset:8192
	s_waitcnt lgkmcnt(4)
	v_mfma_f32_16x16x32_bf16 v[64:67], v[220:223], v[52:55], v[64:67]
	ds_read_b128 v[244:247], v203 offset:8192
	s_waitcnt lgkmcnt(4)
	v_mfma_f32_16x16x32_bf16 v[64:67], v[228:231], v[56:59], v[64:67]
	ds_read_b128 v[248:251], v204 offset:8192
	s_waitcnt lgkmcnt(4)
	v_mfma_f32_16x16x32_bf16 v[64:67], v[232:235], v[60:63], v[64:67]
	ds_read_b128 v[216:219], v197 offset:16384
	s_waitcnt lgkmcnt(4)
	v_mfma_f32_16x16x32_bf16 v[64:67], v[236:239], v[44:47], v[64:67]
	ds_read_b128 v[220:223], v198 offset:16384
	s_waitcnt lgkmcnt(4)
	v_mfma_f32_16x16x32_bf16 v[64:67], v[240:243], v[40:43], v[64:67]
	ds_read_b128 v[228:231], v199 offset:16384
	s_waitcnt lgkmcnt(4)
	v_mfma_f32_16x16x32_bf16 v[64:67], v[244:247], v[36:39], v[64:67]
	ds_read_b128 v[232:235], v200 offset:16384
	s_waitcnt lgkmcnt(4)
	v_mfma_f32_16x16x32_bf16 v[162:165], v[248:251], v[32:35], v[64:67]
	s_nop 5
	ds_read_b128 v[236:239], v201 offset:16384
	s_waitcnt lgkmcnt(4)
	v_mfma_f32_16x16x32_bf16 v[64:67], v[216:219], v[48:51], 0
	ds_read_b128 v[240:243], v202 offset:16384
	s_waitcnt lgkmcnt(4)
	v_mfma_f32_16x16x32_bf16 v[64:67], v[220:223], v[52:55], v[64:67]
	ds_read_b128 v[244:247], v203 offset:16384
	s_waitcnt lgkmcnt(4)
	v_mfma_f32_16x16x32_bf16 v[64:67], v[228:231], v[56:59], v[64:67]
	ds_read_b128 v[248:251], v204 offset:16384
	s_waitcnt lgkmcnt(4)
	v_mfma_f32_16x16x32_bf16 v[64:67], v[232:235], v[60:63], v[64:67]
	ds_read_b128 v[216:219], v197 offset:24576
	s_waitcnt lgkmcnt(4)
	v_mfma_f32_16x16x32_bf16 v[64:67], v[236:239], v[44:47], v[64:67]
	ds_read_b128 v[220:223], v198 offset:24576
	s_waitcnt lgkmcnt(4)
	v_mfma_f32_16x16x32_bf16 v[64:67], v[240:243], v[40:43], v[64:67]
	ds_read_b128 v[228:231], v199 offset:24576
	s_waitcnt lgkmcnt(4)
	v_mfma_f32_16x16x32_bf16 v[64:67], v[244:247], v[36:39], v[64:67]
	ds_read_b128 v[232:235], v200 offset:24576
	s_waitcnt lgkmcnt(4)
	v_mfma_f32_16x16x32_bf16 v[166:169], v[248:251], v[32:35], v[64:67]
	ds_read_b128 v[236:239], v201 offset:24576
	s_waitcnt lgkmcnt(4)
	v_mfma_f32_16x16x32_bf16 v[64:67], v[216:219], v[48:51], 0
	ds_read_b128 v[240:243], v202 offset:24576
	s_waitcnt lgkmcnt(4)
	v_mfma_f32_16x16x32_bf16 v[64:67], v[220:223], v[52:55], v[64:67]
	ds_read_b128 v[244:247], v203 offset:24576
	s_waitcnt lgkmcnt(4)
	v_mfma_f32_16x16x32_bf16 v[64:67], v[228:231], v[56:59], v[64:67]
	ds_read_b128 v[248:251], v204 offset:24576
	s_waitcnt lgkmcnt(4)
	v_mfma_f32_16x16x32_bf16 v[64:67], v[232:235], v[60:63], v[64:67]
	ds_read_b128 v[216:219], v197 offset:32768
	s_waitcnt lgkmcnt(4)
	v_mfma_f32_16x16x32_bf16 v[64:67], v[236:239], v[44:47], v[64:67]
	ds_read_b128 v[220:223], v198 offset:32768
	s_waitcnt lgkmcnt(4)
	v_mfma_f32_16x16x32_bf16 v[64:67], v[240:243], v[40:43], v[64:67]
	ds_read_b128 v[228:231], v199 offset:32768
	s_waitcnt lgkmcnt(4)
	v_mfma_f32_16x16x32_bf16 v[64:67], v[244:247], v[36:39], v[64:67]
	ds_read_b128 v[232:235], v200 offset:32768
	s_waitcnt lgkmcnt(4)
	v_mfma_f32_16x16x32_bf16 v[170:173], v[248:251], v[32:35], v[64:67]
	s_nop 5
	ds_read_b128 v[236:239], v201 offset:32768
	s_waitcnt lgkmcnt(4)
	v_mfma_f32_16x16x32_bf16 v[64:67], v[216:219], v[48:51], 0
	ds_read_b128 v[240:243], v202 offset:32768
	s_waitcnt lgkmcnt(4)
	v_mfma_f32_16x16x32_bf16 v[64:67], v[220:223], v[52:55], v[64:67]
	ds_read_b128 v[244:247], v203 offset:32768
	s_waitcnt lgkmcnt(4)
	v_mfma_f32_16x16x32_bf16 v[64:67], v[228:231], v[56:59], v[64:67]
	ds_read_b128 v[248:251], v204 offset:32768
	s_waitcnt lgkmcnt(4)
	v_mfma_f32_16x16x32_bf16 v[64:67], v[232:235], v[60:63], v[64:67]
	ds_read_b128 v[216:219], v197 offset:40960
	s_waitcnt lgkmcnt(4)
	v_mfma_f32_16x16x32_bf16 v[64:67], v[236:239], v[44:47], v[64:67]
	ds_read_b128 v[220:223], v198 offset:40960
	s_waitcnt lgkmcnt(4)
	v_mfma_f32_16x16x32_bf16 v[64:67], v[240:243], v[40:43], v[64:67]
	ds_read_b128 v[228:231], v199 offset:40960
	s_waitcnt lgkmcnt(4)
	v_mfma_f32_16x16x32_bf16 v[64:67], v[244:247], v[36:39], v[64:67]
	ds_read_b128 v[232:235], v200 offset:40960
	s_waitcnt lgkmcnt(4)
	v_mfma_f32_16x16x32_bf16 v[174:177], v[248:251], v[32:35], v[64:67]
	ds_read_b128 v[236:239], v201 offset:40960
	s_waitcnt lgkmcnt(4)
	v_mfma_f32_16x16x32_bf16 v[64:67], v[216:219], v[48:51], 0
	ds_read_b128 v[240:243], v202 offset:40960
	s_waitcnt lgkmcnt(4)
	v_mfma_f32_16x16x32_bf16 v[64:67], v[220:223], v[52:55], v[64:67]
	ds_read_b128 v[244:247], v203 offset:40960
	s_waitcnt lgkmcnt(4)
	v_mfma_f32_16x16x32_bf16 v[64:67], v[228:231], v[56:59], v[64:67]
	ds_read_b128 v[248:251], v204 offset:40960
	s_waitcnt lgkmcnt(4)
	v_mfma_f32_16x16x32_bf16 v[64:67], v[232:235], v[60:63], v[64:67]
	ds_read_b128 v[216:219], v197 offset:49152
	s_waitcnt lgkmcnt(4)
	v_mfma_f32_16x16x32_bf16 v[64:67], v[236:239], v[44:47], v[64:67]
	ds_read_b128 v[220:223], v197 offset:57344
	s_waitcnt lgkmcnt(4)
	v_mfma_f32_16x16x32_bf16 v[64:67], v[240:243], v[40:43], v[64:67]
	ds_read_b128 v[228:231], v198 offset:49152
	s_waitcnt lgkmcnt(4)
	v_mfma_f32_16x16x32_bf16 v[64:67], v[244:247], v[36:39], v[64:67]
	ds_read_b128 v[232:235], v198 offset:57344
	s_waitcnt lgkmcnt(4)
	v_mfma_f32_16x16x32_bf16 v[178:181], v[248:251], v[32:35], v[64:67]
	s_nop 5
	ds_read_b128 v[236:239], v199 offset:49152
	s_waitcnt lgkmcnt(4)
	v_mfma_f32_16x16x32_bf16 v[64:67], v[216:219], v[48:51], 0
	ds_read_b128 v[240:243], v199 offset:57344
	s_waitcnt lgkmcnt(4)
	v_mfma_f32_16x16x32_bf16 v[48:51], v[220:223], v[48:51], 0
	ds_read_b128 v[244:247], v200 offset:49152
	s_waitcnt lgkmcnt(4)
	v_mfma_f32_16x16x32_bf16 v[64:67], v[228:231], v[52:55], v[64:67]
	ds_read_b128 v[248:251], v200 offset:57344
	s_waitcnt lgkmcnt(4)
	v_mfma_f32_16x16x32_bf16 v[48:51], v[232:235], v[52:55], v[48:51]
	ds_read_b128 v[216:219], v201 offset:49152
	s_waitcnt lgkmcnt(4)
	v_mfma_f32_16x16x32_bf16 v[64:67], v[236:239], v[56:59], v[64:67]
	ds_read_b128 v[220:223], v201 offset:57344
	s_waitcnt lgkmcnt(4)
	v_mfma_f32_16x16x32_bf16 v[48:51], v[240:243], v[56:59], v[48:51]
	ds_read_b128 v[228:231], v202 offset:49152
	s_waitcnt lgkmcnt(4)
	v_mfma_f32_16x16x32_bf16 v[64:67], v[244:247], v[60:63], v[64:67]
	ds_read_b128 v[232:235], v202 offset:57344
	s_waitcnt lgkmcnt(4)
	v_mfma_f32_16x16x32_bf16 v[48:51], v[248:251], v[60:63], v[48:51]
	ds_read_b128 v[236:239], v203 offset:49152
	s_waitcnt lgkmcnt(4)
	v_mfma_f32_16x16x32_bf16 v[64:67], v[216:219], v[44:47], v[64:67]
	ds_read_b128 v[240:243], v203 offset:57344
	s_waitcnt lgkmcnt(4)
	v_mfma_f32_16x16x32_bf16 v[44:47], v[220:223], v[44:47], v[48:51]
	ds_read_b128 v[244:247], v204 offset:49152
	s_waitcnt lgkmcnt(4)
	v_mfma_f32_16x16x32_bf16 v[64:67], v[228:231], v[40:43], v[64:67]
	ds_read_b128 v[248:251], v204 offset:57344
	s_waitcnt lgkmcnt(4)
	v_mfma_f32_16x16x32_bf16 v[40:43], v[232:235], v[40:43], v[44:47]
	s_waitcnt lgkmcnt(3)
	v_mfma_f32_16x16x32_bf16 v[64:67], v[236:239], v[36:39], v[64:67]
	v_lshl_or_b32 v46, s22, 5, v182
	v_lshl_add_u64 v[44:45], s[26:27], 0, v[184:185]
	s_waitcnt lgkmcnt(2)
	v_mfma_f32_16x16x32_bf16 v[36:39], v[240:243], v[36:39], v[40:43]
	s_nop 2
	v_mad_i64_i32 v[40:41], s[26:27], v46, s42, v[44:45]
	v_or_b32_e32 v46, 16, v46
	v_mad_i64_i32 v[44:45], s[26:27], v46, s42, v[44:45]
	s_waitcnt lgkmcnt(1)
	v_mfma_f32_16x16x32_bf16 v[210:213], v[244:247], v[32:35], v[64:67]
	global_load_dwordx4 v[136:139], v[40:41], off
	global_load_dwordx4 v[120:123], v[40:41], off offset:64
	global_load_dwordx4 v[108:111], v[40:41], off offset:128
	global_load_dwordx4 v[100:103], v[40:41], off offset:192
	global_load_dwordx4 v[92:95], v[40:41], off offset:256
	global_load_dwordx4 v[84:87], v[40:41], off offset:320
	global_load_dwordx4 v[80:83], v[40:41], off offset:384
	global_load_dwordx4 v[76:79], v[40:41], off offset:448
	global_load_dwordx4 v[72:75], v[40:41], off offset:512
	global_load_dwordx4 v[68:71], v[40:41], off offset:576
	global_load_dwordx4 v[64:67], v[40:41], off offset:640
	s_nop 0
	global_load_dwordx4 v[40:43], v[40:41], off offset:704
	s_nop 0
	global_load_dwordx4 v[152:155], v[44:45], off
	global_load_dwordx4 v[148:151], v[44:45], off offset:64
	global_load_dwordx4 v[144:147], v[44:45], off offset:128
	global_load_dwordx4 v[140:143], v[44:45], off offset:192
	global_load_dwordx4 v[132:135], v[44:45], off offset:256
	global_load_dwordx4 v[128:131], v[44:45], off offset:320
	global_load_dwordx4 v[124:127], v[44:45], off offset:384
	global_load_dwordx4 v[116:119], v[44:45], off offset:448
	global_load_dwordx4 v[112:115], v[44:45], off offset:512
	global_load_dwordx4 v[104:107], v[44:45], off offset:576
	global_load_dwordx4 v[96:99], v[44:45], off offset:640
	global_load_dwordx4 v[88:91], v[44:45], off offset:704
	s_waitcnt lgkmcnt(0)
	v_mfma_f32_16x16x32_bf16 v[32:35], v[248:251], v[32:35], v[36:39]
	s_nop 2
	v_lshlrev_b32_e32 v36, 11, v156
	v_lshlrev_b32_e32 v37, 2, v182
	v_add3_u32 v36, s52, v37, v36
	ds_write2st64_b32 v36, v158, v159 offset1:2
	ds_write2st64_b32 v36, v160, v161 offset0:4 offset1:6
	ds_write2st64_b32 v36, v162, v163 offset0:32 offset1:34
	ds_write2st64_b32 v36, v164, v165 offset0:36 offset1:38
	ds_write2st64_b32 v36, v166, v167 offset0:64 offset1:66
	ds_write2st64_b32 v36, v168, v169 offset0:68 offset1:70
	ds_write2st64_b32 v36, v170, v171 offset0:96 offset1:98
	ds_write2st64_b32 v36, v172, v173 offset0:100 offset1:102
	ds_write2st64_b32 v36, v174, v175 offset0:128 offset1:130
	ds_write2st64_b32 v36, v176, v177 offset0:132 offset1:134
	ds_write2st64_b32 v36, v178, v179 offset0:160 offset1:162
	ds_write2st64_b32 v36, v180, v181 offset0:164 offset1:166
	ds_write2st64_b32 v36, v210, v211 offset0:192 offset1:194
	ds_write2st64_b32 v36, v212, v213 offset0:196 offset1:198
	ds_write2st64_b32 v36, v32, v33 offset0:224 offset1:226
	ds_write2st64_b32 v36, v34, v35 offset0:228 offset1:230
	s_cbranch_scc1 .LBB0_498
	s_lshl_b64 s[26:27], s[0:1], 16
	s_add_u32 s0, s14, s26
	s_addc_u32 s27, s15, s27
	s_lshl_b32 s26, s44, 20
	s_and_b32 s26, s26, 0x1f00000
	s_add_u32 s26, s0, s26
	s_addc_u32 s27, s27, 0
	v_lshl_add_u64 v[24:25], v[186:187], 4, s[26:27]
	v_add_co_u32_e32 v4, vcc, s25, v24
	s_nop 1
	v_addc_co_u32_e32 v5, vcc, 0, v25, vcc
	v_add_co_u32_e32 v8, vcc, s36, v24
	global_load_dwordx4 v[0:3], v[24:25], off nt
	s_nop 0
	global_load_dwordx4 v[4:7], v[4:5], off nt
	v_addc_co_u32_e32 v9, vcc, 0, v25, vcc
	v_add_co_u32_e32 v12, vcc, s37, v24
	s_nop 1
	v_addc_co_u32_e32 v13, vcc, 0, v25, vcc
	v_add_co_u32_e32 v16, vcc, s38, v24
	global_load_dwordx4 v[8:11], v[8:9], off nt
	s_nop 0
	global_load_dwordx4 v[12:15], v[12:13], off nt
	v_addc_co_u32_e32 v17, vcc, 0, v25, vcc
	v_add_co_u32_e32 v20, vcc, s39, v24
	s_nop 1
	v_addc_co_u32_e32 v21, vcc, 0, v25, vcc
	v_add_co_u32_e32 v26, vcc, s40, v24
	global_load_dwordx4 v[16:19], v[16:17], off nt
	s_nop 0
	global_load_dwordx4 v[20:23], v[20:21], off nt
	v_addc_co_u32_e32 v27, vcc, 0, v25, vcc
	v_add_co_u32_e32 v28, vcc, s41, v24
	s_nop 1
	v_addc_co_u32_e32 v29, vcc, 0, v25, vcc
	global_load_dwordx4 v[24:27], v[26:27], off nt
	s_nop 0
	global_load_dwordx4 v[28:31], v[28:29], off nt
